# plus s_setprio 2 for phase-2 chunk-precompute workers (scan start-up items finish sooner)
# speedup vs baseline: 1.0135x; 1.0017x over previous
; __device__ __forceinline__ int ltid() { int t = threadIdx.x; asm volatile("" : "+v"(t)); return t; }
; template <bool SIGNAL>
; __device__ __forceinline__ void phase2(const Params& p, unsigned char* smem, const int lo, const int hi, const int worker, const int nworkers) {
;   u16* DX = (u16*)(p.ws + OFF_DX); const u16* HALO = (const u16*)(p.ws + OFF_HALO);
;   const float* BETA = (const float*)(p.ws + OFF_BETA); const float* GG = (const float*)(p.ws + OFF_G);
;   u16* TA = (u16*)(p.ws + OFF_EXTRA);
;   float* sin = (float*)smem;
;   u16* sq = (u16*)(smem + 34304);
;   u16* sk = sq + 64 * 136;
;   u16* svT = sq;
;   float* sgc = (float*)(smem + 34304 + 34816);
;   float* sbeta = sgc + 64;
;   float* sM = (float*)smem;
;   const int tid = ltid(), lane = tid & 63, wave = tid >> 6;
;   const int l31 = lane & 31, hf = lane >> 5;
;   for (int idx2 = lo + worker; idx2 < hi; idx2 += nworkers) {
;     const int bh = idx2 & 15, c = idx2 >> 4; const int it = bh * NCH + c; const int h = bh & 7;
; __device__ __forceinline__ void phase3(const Params& p, unsigned char* smem, unsigned* bar) {
;     ...
;   const bool is_scan = (blockIdx.x < 16);
;   if (is_scan) {
;     f32x16 S[4];
; #pragma unroll
;     for (int d = 0; d < 4; ++d)
; #pragma unroll
;       for (int r = 0; r < 16; ++r) S[d][r] = 0.f;
;     scan_chunked(p, smem, blockIdx.x, S, 0, NCH);
;   } else {
;     phase2<true>(p, smem, P2_SPLIT * 16, NCH * 16, blockIdx.x - 16, gridDim.x - 16);
.LBB0_250:
	s_or_b64 exec, exec, s[4:5]
	v_mov_b32_e32 v220, v218
	v_writelane_b32 v247, s12, 0
	s_cmp_gt_u32 s89, 15
	s_mov_b64 s[4:5], -1
	v_writelane_b32 v247, s13, 1
	s_barrier
	s_cbranch_scc0 .LBB0_311
	s_add_i32 s84, s89, -16
	v_mov_b32_e32 v32, v218
	s_add_i32 s2, s3, -16
	s_min_u32 s2, s2, 0x120
	s_cmp_ge_i32 s84, s2
	v_writelane_b32 v247, s73, 2
	s_cbranch_scc1 .LBB0_310
	s_setprio 2
	s_load_dwordx2 s[6:7], s[0:1], 0x90
	v_lshlrev_b32_e32 v7, 3, v32
	v_and_b32_e32 v0, 0x78, v7
	v_mov_b32_e32 v35, 0
	v_lshlrev_b32_e32 v34, 1, v0
	s_waitcnt lgkmcnt(0)
	s_add_u32 s85, s6, 0x6090000
	s_addc_u32 s86, s7, 0
	s_add_u32 s2, s6, 0xee1d000
	v_writelane_b32 v247, s2, 3
	s_addc_u32 s2, s7, 0
	v_writelane_b32 v247, s2, 4
	s_add_u32 s2, s6, 0xee9e000
	v_writelane_b32 v247, s2, 5
	s_addc_u32 s2, s7, 0
	v_writelane_b32 v247, s2, 6
	s_add_u32 s2, s6, 0xc5d9000
	v_writelane_b32 v247, s2, 7
	s_addc_u32 s2, s7, 0
	v_lshl_add_u64 v[4:5], s[6:7], 0, v[34:35]
	s_mov_b64 s[12:13], 0xc150000
	v_writelane_b32 v247, s2, 8
	v_lshl_add_u64 v[36:37], v[4:5], 0, s[12:13]
	v_cmp_gt_i32_e64 s[12:13], 64, v32
	v_and_b32_e32 v39, 63, v32
	v_ashrrev_i32_e32 v2, 6, v32
	v_writelane_b32 v247, s12, 9
	v_and_b32_e32 v1, 31, v32
	v_and_b32_e32 v38, 56, v7
	v_writelane_b32 v247, s13, 10
	v_cmp_eq_u32_e64 s[12:13], 0, v32
	v_lshlrev_b32_e32 v7, 5, v2
	v_and_or_b32 v1, v7, 32, v1
	v_writelane_b32 v247, s12, 11
	s_movk_i32 s11, 0x110
	v_ashrrev_i32_e32 v13, 2, v32
	v_writelane_b32 v247, s13, 12
	v_cmp_eq_u32_e64 s[12:13], 0, v39
	s_movk_i32 s8, 0xffe0
	v_bfe_u32 v6, v32, 5, 1
	v_writelane_b32 v247, s12, 13
	v_mad_u32_u24 v11, v1, s11, 16
	v_and_b32_e32 v14, 0xffffffe0, v13
	v_writelane_b32 v247, s13, 14
	v_cmp_gt_u32_e64 s[12:13], 2, v39
	v_bfi_b32 v13, s8, v13, v32
	s_movk_i32 s8, 0xfef4
	v_writelane_b32 v247, s12, 15
	v_mul_u32_u24_e32 v4, 0x118, v39
	v_lshlrev_b32_e32 v5, 3, v39
	v_writelane_b32 v247, s13, 16
	v_cmp_gt_u32_e64 s[12:13], 4, v39
	v_lshl_add_u32 v10, v38, 1, 16
	v_lshlrev_b32_e32 v12, 4, v6
	v_writelane_b32 v247, s12, 17
	v_lshl_or_b32 v20, v6, 2, v14
	v_mad_i32_i24 v6, v1, s8, v11
	v_writelane_b32 v247, s13, 18
	v_cmp_gt_u32_e64 s[12:13], 8, v39
	s_movk_i32 s8, 0x10e
	v_add3_u32 v9, 16, v5, v4
	v_writelane_b32 v247, s12, 19
	v_add_u32_e32 v108, v11, v12
	v_lshlrev_b32_e32 v11, 4, v39
	v_writelane_b32 v247, s13, 20
	v_cmp_gt_u32_e64 s[12:13], 16, v39
	v_mad_u32_u24 v21, v38, s8, v10
	s_movk_i32 s8, 0x42f
	v_writelane_b32 v247, s12, 21
	s_add_i32 s9, 16, 0x10e00
	s_add_i32 s10, 16, 0x10f00
	v_writelane_b32 v247, s13, 22
	v_cmp_gt_u32_e64 s[12:13], 32, v39
	v_sub_u32_e32 v111, v9, v11
	v_lshlrev_b32_e32 v9, 2, v32
	v_writelane_b32 v247, s12, 23
	v_add_u32_e32 v112, s9, v9
	v_add_u32_e32 v113, s10, v9
	v_writelane_b32 v247, s13, 24
	v_cmp_lt_i32_e64 s[12:13], s8, v32
	v_ashrrev_i32_e32 v9, 4, v32
	s_movk_i32 s8, 0x32f
	v_writelane_b32 v247, s12, 25
	v_cmp_gt_i32_e64 s[26:27], 3, v9
	v_lshlrev_b32_e32 v42, 7, v9
	v_writelane_b32 v247, s13, 26
	v_cmp_gt_i32_e64 s[12:13], 51, v9
	v_add_u32_e32 v9, 0x100, v32
	v_ashrrev_i32_e32 v11, 4, v9
	v_writelane_b32 v247, s12, 27
	v_mul_lo_u32 v13, v13, s11
	v_cmp_gt_i32_e64 s[34:35], 3, v11
	v_writelane_b32 v247, s13, 28
	v_cmp_lt_i32_e64 s[12:13], s8, v32
	s_movk_i32 s8, 0x22f
	v_lshlrev_b32_e32 v46, 7, v11
	v_writelane_b32 v247, s12, 29
	v_add3_u32 v109, 16, v13, v12
	v_lshl_add_u32 v8, v0, 2, 16
	v_writelane_b32 v247, s13, 30
	v_cmp_gt_i32_e64 s[12:13], 51, v11
	v_add_u32_e32 v11, 0x200, v32
	v_ashrrev_i32_e32 v12, 4, v11
	v_writelane_b32 v247, s12, 31
	v_cmp_gt_i32_e64 s[40:41], 3, v12
	v_lshlrev_b32_e32 v50, 7, v12
	v_writelane_b32 v247, s13, 32
	v_cmp_lt_i32_e64 s[12:13], s8, v32
	s_movk_i32 s8, 0x12f
	v_ashrrev_i32_e32 v22, 3, v32
	v_writelane_b32 v247, s12, 33
	v_ashrrev_i32_e32 v23, 3, v9
	v_lshlrev_b32_e32 v62, 6, v22
	v_writelane_b32 v247, s13, 34
	v_cmp_gt_i32_e64 s[12:13], 51, v12
	v_add_u32_e32 v12, 0x300, v32
	v_ashrrev_i32_e32 v13, 4, v12
	v_writelane_b32 v247, s12, 35
	v_cmp_gt_i32_e64 s[46:47], 3, v13
	v_lshlrev_b32_e32 v54, 7, v13
	v_writelane_b32 v247, s13, 36
	v_cmp_lt_i32_e64 s[12:13], s8, v32
	s_movk_i32 s8, 0x430
	v_cmp_gt_i32_e64 s[54:55], s8, v32
	v_writelane_b32 v247, s12, 37
	s_movk_i32 s8, 0x330
	v_cmp_gt_i32_e64 s[56:57], s8, v32
	v_writelane_b32 v247, s13, 38
	v_cmp_gt_i32_e64 s[12:13], 51, v13
	v_add_u32_e32 v13, 0x400, v32
	v_ashrrev_i32_e32 v14, 4, v13
	v_writelane_b32 v247, s12, 39
	v_cmp_gt_i32_e64 s[52:53], 3, v14
	v_lshlrev_b32_e32 v58, 7, v14
	v_writelane_b32 v247, s13, 40
	v_cmp_lt_i32_e64 s[12:13], 47, v32
	s_movk_i32 s8, 0x230
	v_lshlrev_b32_e32 v13, 5, v13
	v_writelane_b32 v247, s12, 41
	v_cmp_gt_i32_e64 s[58:59], s8, v32
	s_movk_i32 s8, 0x130
	v_writelane_b32 v247, s13, 42
	v_cmp_gt_i32_e64 s[12:13], 51, v14
	v_lshlrev_b32_e32 v14, 5, v32
	v_and_b32_e32 v14, 0xfffffe00, v14
	v_add_u32_e32 v114, v8, v14
	v_lshlrev_b32_e32 v14, 5, v9
	v_and_b32_e32 v14, 0xfffffe00, v14
	v_add_u32_e32 v115, v8, v14
	v_lshlrev_b32_e32 v14, 5, v11
	v_and_b32_e32 v14, 0xfffffe00, v14
	v_writelane_b32 v247, s12, 43
	v_add_u32_e32 v116, v8, v14
	v_lshlrev_b32_e32 v14, 5, v12
	v_writelane_b32 v247, s13, 44
	v_and_b32_e32 v14, 0xfffffe00, v14
	v_and_b32_e32 v13, 0xfffffe00, v13
	s_movk_i32 s12, 0x90
	v_cmp_gt_i32_e64 s[60:61], s8, v32
	v_add_u32_e32 v117, v8, v14
	v_add_u32_e32 v118, v8, v13
	v_mul_lo_u32 v8, v22, s12
	s_mov_b32 s8, 0x8600
	v_add3_u32 v119, v10, v8, s8
	v_mul_lo_u32 v8, v23, s12
	v_add3_u32 v120, v10, v8, s8
	v_ashrrev_i32_e32 v8, 3, v11
	v_mul_lo_u32 v9, v8, s12
	s_waitcnt vmcnt(6)
; __device__ __forceinline__ float bflo(unsigned v) { return __uint_as_float(v << 16); }
; template <bool SIGNAL>
; __device__ __forceinline__ void phase2(const Params& p, unsigned char* smem, const int lo, const int hi, const int worker, const int nworkers) {
;     ...
;   const int tid = ltid(), lane = tid & 63, wave = tid >> 6;
;   const int l31 = lane & 31, hf = lane >> 5;
;   for (int idx2 = lo + worker; idx2 < hi; idx2 += nworkers) {
;     const int bh = idx2 & 15, c = idx2 >> 4; const int it = bh * NCH + c; const int h = bh & 7;
;     if (wave == 0) {
;       const bool pad = (c == 0 && lane < 48);
;       float g = pad ? 0.f : GG[(size_t)bh * LPAD + c * 64 + lane];
;       float be = pad ? 0.f : BETA[(size_t)bh * LPAD + c * 64 + lane];
; #pragma unroll
;       for (int o = 1; o < 64; o <<= 1) { float t = __shfl_up(g, o); if (lane >= o) g += t; }
;       sgc[lane] = g; sbeta[lane] = be;
;     }
;     for (int wi = 0; wi < 3; ++wi) {
;       const int which = wi == 0 ? 2 : wi - 1;
;       u16* X = DX + ((size_t)it * 3 + which) * 8192;
;       const u16* H = HALO + ((size_t)(it - 1) * 3 + which) * 384;
;       {
;         u32x4 ld[5];
; #pragma unroll
;         for (int i = 0; i < 5; ++i) {
;           const int idx = tid + 256 * i; const int rr = idx >> 4, c8 = (idx & 15) * 8; const int r = rr - 3;
;           const bool zero = (idx >= 67 * 16) || (c == 0 && r < 48);
;           const u16* srcp = (r < 0) ? (H + rr * 128 + c8) : (X + r * 128 + c8);
;           u32x4 z = {0u, 0u, 0u, 0u};
;           ld[i] = zero ? z : *(const u32x4*)srcp;
;         }
; #pragma unroll
;         for (int i = 0; i < 5; ++i) {
;           const int idx = tid + 256 * i; const int rr = idx >> 4, c8 = (idx & 15) * 8;
;           if (idx < 67 * 16) {
;             float4 a = make_float4(bflo(ld[i].x), bfhi(ld[i].x), bflo(ld[i].y), bfhi(ld[i].y));
;             float4 b = make_float4(bflo(ld[i].z), bfhi(ld[i].z), bflo(ld[i].w), bfhi(ld[i].w));
;             *(float4*)(sin + rr * 128 + c8) = a; *(float4*)(sin + rr * 128 + c8 + 4) = b;
;           }
;         }
;       }
;       __syncthreads();
;       const int d0 = 2 * lane; const int ch = which * 1024 + h * 128 + d0;
;       float w0[4], w1[4];
; #pragma unroll
;       for (int j = 0; j < 4; ++j) { w0[j] = p.conv_w[j * 3072 + ch]; w1[j] = p.conv_w[j * 3072 + ch + 1]; }
	v_lshlrev_b32_e32 v66, 6, v8
	v_ashrrev_i32_e32 v8, 3, v12
	v_add3_u32 v121, v10, v9, s8
	v_mul_lo_u32 v9, v8, s12
	v_cmp_lt_i32_e64 s[12:13], v1, v20
	v_add3_u32 v122, v10, v9, s8
	v_or_b32_e32 v9, 1, v20
	v_writelane_b32 v247, s12, 45
	v_lshlrev_b32_e32 v10, 2, v9
	s_waitcnt vmcnt(5)
	v_lshl_or_b32 v72, v9, 6, v1
	v_writelane_b32 v247, s13, 46
	v_cmp_gt_i32_e64 s[12:13], v1, v9
	v_or_b32_e32 v9, 2, v20
	v_add_u32_e32 v125, s9, v10
	v_writelane_b32 v247, s12, 47
	v_add_u32_e32 v126, s10, v10
	v_lshlrev_b32_e32 v10, 2, v9
	v_writelane_b32 v247, s13, 48
	v_cmp_lt_i32_e64 s[12:13], v1, v9
	v_lshl_or_b32 v74, v9, 6, v1
	v_add_u32_e32 v127, s9, v10
	v_writelane_b32 v247, s12, 49
	v_add_u32_e32 v128, s10, v10
	v_lshlrev_b32_e32 v68, 6, v8
	v_writelane_b32 v247, s13, 50
	v_cmp_gt_i32_e64 s[12:13], v1, v9
	v_or_b32_e32 v9, 3, v20
	v_lshlrev_b32_e32 v10, 2, v9
	v_writelane_b32 v247, s12, 51
	s_waitcnt vmcnt(3)
	v_lshl_or_b32 v76, v9, 6, v1
	v_add_u32_e32 v129, s9, v10
	v_writelane_b32 v247, s13, 52
	v_cmp_lt_i32_e64 s[12:13], v1, v9
	v_add_u32_e32 v130, s10, v10
	v_lshlrev_b32_e32 v8, 2, v20
	v_writelane_b32 v247, s12, 53
	v_add_u32_e32 v123, s9, v8
	v_add_u32_e32 v124, s10, v8
	v_writelane_b32 v247, s13, 54
	v_cmp_gt_i32_e64 s[12:13], v1, v9
	v_or_b32_e32 v9, 8, v20
	v_lshlrev_b32_e32 v10, 2, v9
	v_add_u32_e32 v131, s9, v10
	v_add_u32_e32 v132, s10, v10
	v_or_b32_e32 v10, 9, v20
	v_lshlrev_b32_e32 v11, 2, v10
	v_add_u32_e32 v133, s9, v11
	v_add_u32_e32 v134, s10, v11
	v_or_b32_e32 v11, 10, v20
	v_lshlrev_b32_e32 v12, 2, v11
	v_add_u32_e32 v135, s9, v12
	v_add_u32_e32 v136, s10, v12
	v_or_b32_e32 v12, 11, v20
	v_lshlrev_b32_e32 v13, 2, v12
	v_add_u32_e32 v137, s9, v13
	v_add_u32_e32 v138, s10, v13
	v_or_b32_e32 v13, 16, v20
	v_lshlrev_b32_e32 v14, 2, v13
	v_add_u32_e32 v139, s9, v14
	v_add_u32_e32 v140, s10, v14
	v_or_b32_e32 v14, 17, v20
	v_lshlrev_b32_e32 v15, 2, v14
	v_add_u32_e32 v141, s9, v15
	v_add_u32_e32 v142, s10, v15
	v_or_b32_e32 v15, 18, v20
	v_lshlrev_b32_e32 v16, 2, v15
	v_add_u32_e32 v143, s9, v16
	v_add_u32_e32 v144, s10, v16
	v_or_b32_e32 v16, 19, v20
	v_lshlrev_b32_e32 v17, 2, v16
	v_add_u32_e32 v145, s9, v17
	v_add_u32_e32 v146, s10, v17
	v_or_b32_e32 v17, 24, v20
	v_lshlrev_b32_e32 v18, 2, v17
	v_add_u32_e32 v147, s9, v18
	v_add_u32_e32 v148, s10, v18
	v_or_b32_e32 v18, 25, v20
	v_lshlrev_b32_e32 v19, 2, v18
	v_writelane_b32 v247, s12, 55
	v_add_u32_e32 v149, s9, v19
	v_add_u32_e32 v150, s10, v19
	v_or_b32_e32 v19, 26, v20
	v_mul_lo_u32 v8, v20, s11
	v_cmp_gt_i32_e64 s[66:67], v1, v20
	v_lshl_or_b32 v70, v20, 6, v1
	v_writelane_b32 v247, s13, 56
	v_cmp_lt_i32_e64 s[12:13], v1, v9
	v_lshlrev_b32_e32 v24, 2, v19
	v_or_b32_e32 v20, 27, v20
	v_lshl_add_u32 v155, v22, 2, v21
	v_lshlrev_b32_e32 v22, 11, v2
	v_lshlrev_b32_e32 v3, 2, v39
	s_movk_i32 s2, 0x118
	v_lshlrev_b32_e32 v64, 6, v23
	v_writelane_b32 v247, s12, 57
	v_add_u32_e32 v151, s9, v24
	v_add_u32_e32 v152, s10, v24
	v_lshlrev_b32_e32 v24, 2, v20
	v_lshl_add_u32 v156, v23, 2, v21
	v_ashrrev_i32_e32 v23, 31, v22
	v_add_u32_e32 v104, s9, v3
	v_lshl_add_u32 v110, v1, 2, s9
	v_writelane_b32 v247, s13, 58
	v_add_u32_e32 v153, s9, v24
	s_add_i32 s9, s3, -16
	s_min_u32 s9, s9, 0x120
	v_mad_u32_u24 v7, v39, s2, v7
	s_movk_i32 s2, 0x1100
	v_lshlrev_b64 v[22:23], 1, v[22:23]
	v_writelane_b32 v247, s9, 59
	s_add_u32 s9, s6, 0xf223840
	v_add3_u32 v157, v7, v5, s8
	v_mul_lo_u32 v7, v2, s2
	v_or_b32_e32 v22, v22, v3
	v_cmp_gt_u32_e32 vcc, 48, v39
	v_add_u32_e32 v105, s10, v3
	v_lshlrev_b32_e32 v107, 4, v2
	v_writelane_b32 v247, s9, 60
	s_addc_u32 s9, s7, 0
	v_or_b32_e32 v158, v7, v3
	v_lshl_or_b32 v160, v2, 13, v5
	v_lshl_add_u64 v[2:3], s[6:7], 0, v[22:23]
	s_mov_b64 s[6:7], 0x6090200
	v_writelane_b32 v247, s9, 61
	v_lshl_add_u64 v[102:103], v[2:3], 0, s[6:7]
	s_xor_b64 s[6:7], vcc, -1
	v_writelane_b32 v247, s6, 62
	s_add_i32 s2, 16, 0x10efc
	v_sub_u32_e32 v2, v4, v5
	v_writelane_b32 v247, s7, 63
	v_writelane_b32 v246, s2, 0
	v_cmp_gt_i32_e64 s[6:7], v1, v9
	v_lshl_or_b32 v78, v9, 6, v1
	v_lshl_or_b32 v80, v10, 6, v1
	v_writelane_b32 v246, s6, 1
	v_lshl_or_b32 v82, v11, 6, v1
	s_waitcnt vmcnt(2)
; __device__ __forceinline__ float bflo(unsigned v) { return __uint_as_float(v << 16); }
; template <bool SIGNAL>
; __device__ __forceinline__ void phase2(const Params& p, unsigned char* smem, const int lo, const int hi, const int worker, const int nworkers) {
;     ...
;   const int tid = ltid(), lane = tid & 63, wave = tid >> 6;
;   const int l31 = lane & 31, hf = lane >> 5;
;   for (int idx2 = lo + worker; idx2 < hi; idx2 += nworkers) {
;     const int bh = idx2 & 15, c = idx2 >> 4; const int it = bh * NCH + c; const int h = bh & 7;
;     if (wave == 0) {
;       const bool pad = (c == 0 && lane < 48);
;       float g = pad ? 0.f : GG[(size_t)bh * LPAD + c * 64 + lane];
;       float be = pad ? 0.f : BETA[(size_t)bh * LPAD + c * 64 + lane];
; #pragma unroll
;       for (int o = 1; o < 64; o <<= 1) { float t = __shfl_up(g, o); if (lane >= o) g += t; }
;       sgc[lane] = g; sbeta[lane] = be;
;     }
;     for (int wi = 0; wi < 3; ++wi) {
;       const int which = wi == 0 ? 2 : wi - 1;
;       u16* X = DX + ((size_t)it * 3 + which) * 8192;
;       const u16* H = HALO + ((size_t)(it - 1) * 3 + which) * 384;
;       {
;         u32x4 ld[5];
; #pragma unroll
;         for (int i = 0; i < 5; ++i) {
;           const int idx = tid + 256 * i; const int rr = idx >> 4, c8 = (idx & 15) * 8; const int r = rr - 3;
;           const bool zero = (idx >= 67 * 16) || (c == 0 && r < 48);
;           const u16* srcp = (r < 0) ? (H + rr * 128 + c8) : (X + r * 128 + c8);
;           u32x4 z = {0u, 0u, 0u, 0u};
;           ld[i] = zero ? z : *(const u32x4*)srcp;
;         }
; #pragma unroll
;         for (int i = 0; i < 5; ++i) {
;           const int idx = tid + 256 * i; const int rr = idx >> 4, c8 = (idx & 15) * 8;
;           if (idx < 67 * 16) {
;             float4 a = make_float4(bflo(ld[i].x), bfhi(ld[i].x), bflo(ld[i].y), bfhi(ld[i].y));
;             float4 b = make_float4(bflo(ld[i].z), bfhi(ld[i].z), bflo(ld[i].w), bfhi(ld[i].w));
;             *(float4*)(sin + rr * 128 + c8) = a; *(float4*)(sin + rr * 128 + c8 + 4) = b;
;           }
;         }
;       }
;       __syncthreads();
;       const int d0 = 2 * lane; const int ch = which * 1024 + h * 128 + d0;
;       float w0[4], w1[4];
; #pragma unroll
;       for (int j = 0; j < 4; ++j) { w0[j] = p.conv_w[j * 3072 + ch]; w1[j] = p.conv_w[j * 3072 + ch + 1]; }
	v_lshl_or_b32 v84, v12, 6, v1
	v_writelane_b32 v246, s7, 2
	v_cmp_lt_i32_e64 s[6:7], v1, v10
	v_lshl_or_b32 v86, v13, 6, v1
	s_waitcnt vmcnt(1)
	v_lshl_or_b32 v88, v14, 6, v1
	v_writelane_b32 v246, s6, 3
	v_lshl_or_b32 v90, v15, 6, v1
	s_waitcnt vmcnt(0)
	v_lshl_or_b32 v92, v16, 6, v1
	v_writelane_b32 v246, s7, 4
	v_cmp_gt_i32_e64 s[6:7], v1, v10
	v_lshl_or_b32 v94, v17, 6, v1
	v_lshl_or_b32 v96, v18, 6, v1
	v_writelane_b32 v246, s6, 5
	v_lshl_or_b32 v98, v19, 6, v1
	v_lshl_or_b32 v100, v20, 6, v1
	v_writelane_b32 v246, s7, 6
	v_cmp_lt_i32_e64 s[6:7], v1, v11
	v_add_u32_e32 v2, 16, v2
	v_cmp_gt_u32_e64 s[4:5], 64, v32
	v_writelane_b32 v246, s6, 7
	v_mov_b32_e32 v33, v35
	v_lshlrev_b32_e32 v106, 1, v39
	v_writelane_b32 v246, s7, 8
	v_cmp_gt_i32_e64 s[6:7], v1, v11
	v_ashrrev_i32_e32 v41, 31, v32
	v_mov_b32_e32 v40, v32
	v_writelane_b32 v246, s6, 9
	v_add_u32_e32 v44, 0xfffffe80, v42
	v_mov_b32_e32 v45, v35
	v_writelane_b32 v246, s7, 10
	v_cmp_lt_i32_e64 s[6:7], v1, v12
	v_ashrrev_i32_e32 v43, 31, v42
	v_add_u32_e32 v48, 0xfffffe80, v46
	v_writelane_b32 v246, s6, 11
	v_mov_b32_e32 v49, v35
	v_ashrrev_i32_e32 v47, 31, v46
	v_writelane_b32 v246, s7, 12
	v_cmp_gt_i32_e64 s[6:7], v1, v12
	v_add_u32_e32 v52, 0xfffffe80, v50
	v_mov_b32_e32 v53, v35
	v_writelane_b32 v246, s6, 13
	v_ashrrev_i32_e32 v51, 31, v50
	v_add_u32_e32 v56, 0xfffffe80, v54
	v_writelane_b32 v246, s7, 14
	v_cmp_lt_i32_e64 s[6:7], v1, v13
	v_mov_b32_e32 v57, v35
	v_ashrrev_i32_e32 v55, 31, v54
	v_writelane_b32 v246, s6, 15
	v_add_u32_e32 v60, 0xfffffe80, v58
	v_mov_b32_e32 v61, v35
	v_writelane_b32 v246, s7, 16
	v_cmp_gt_i32_e64 s[6:7], v1, v13
	v_ashrrev_i32_e32 v59, 31, v58
	v_cmp_gt_i32_e64 s[62:63], 48, v32
	v_writelane_b32 v246, s6, 17
	v_ashrrev_i32_e32 v63, 31, v62
	v_ashrrev_i32_e32 v65, 31, v64
	v_writelane_b32 v246, s7, 18
	v_cmp_lt_i32_e64 s[6:7], v1, v14
	v_ashrrev_i32_e32 v67, 31, v66
	v_ashrrev_i32_e32 v69, 31, v68
	v_writelane_b32 v246, s6, 19
	v_ashrrev_i32_e32 v71, 31, v70
	v_ashrrev_i32_e32 v73, 31, v72
	v_writelane_b32 v246, s7, 20
	v_cmp_gt_i32_e64 s[6:7], v1, v14
	v_ashrrev_i32_e32 v75, 31, v74
	v_ashrrev_i32_e32 v77, 31, v76
	v_writelane_b32 v246, s6, 21
	v_ashrrev_i32_e32 v79, 31, v78
	v_ashrrev_i32_e32 v81, 31, v80
	v_ashrrev_i32_e32 v83, 31, v82
	v_ashrrev_i32_e32 v85, 31, v84
	v_ashrrev_i32_e32 v87, 31, v86
	v_ashrrev_i32_e32 v89, 31, v88
	v_ashrrev_i32_e32 v91, 31, v90
	v_ashrrev_i32_e32 v93, 31, v92
	v_ashrrev_i32_e32 v95, 31, v94
	v_ashrrev_i32_e32 v97, 31, v96
	v_ashrrev_i32_e32 v99, 31, v98
	v_add_u32_e32 v154, s10, v24
	v_ashrrev_i32_e32 v101, 31, v100
	v_and_b32_e32 v159, 0xffffffc0, v32
	v_add_u32_e32 v161, 0x8600, v2
	v_lshlrev_b32_e32 v34, 1, v0
	s_add_i32 s87, 16, 0xca00
	s_mov_b32 s88, 0x800000
	v_add_u32_e32 v162, v6, v8
	v_mbcnt_hi_u32_b32 v163, -1, v219
	v_mov_b32_e32 v164, 0x300
	v_mov_b32_e32 v165, 0x3db504f3
	s_mov_b32 s2, s89
	v_writelane_b32 v246, s7, 22
	v_cmp_lt_i32_e64 s[10:11], v1, v15
	v_cmp_gt_i32_e64 s[12:13], v1, v15
	v_cmp_lt_i32_e64 s[14:15], v1, v16
	v_cmp_gt_i32_e64 s[16:17], v1, v16
	v_cmp_lt_i32_e64 s[18:19], v1, v17
	v_cmp_gt_i32_e64 s[20:21], v1, v17
	v_cmp_lt_i32_e64 s[6:7], v1, v18
	v_cmp_gt_i32_e64 s[8:9], v1, v18
	v_cmp_lt_i32_e64 s[22:23], v1, v19
	v_cmp_gt_i32_e64 s[24:25], v1, v19
	v_cmp_lt_i32_e64 s[28:29], v1, v20
	v_cmp_gt_i32_e64 s[30:31], v1, v20
	s_mov_b32 s64, 0x358637bd
	s_branch .LBB0_254
